# placement trial: post-NA code shifted +32 B relative to the 4 KiB-matched variant
# speedup vs baseline: 1.0045x; 1.0045x over previous
; template <int KIND> ...
;     ...
;             if (t + 1 < nt) ATT_STORE((t + 1) & 1);
;             __syncthreads();
;         }
nap1_164:
	s_cmp_eq_u32 s95, s81
	v_add_u32_e32 v237, 0x7c, v237
	s_waitcnt lgkmcnt(0)
	s_barrier
	s_cbranch_scc1 .LBB0_125
	s_mov_b32 s83, s81
	s_branch nap1_145
	s_nop 0
	s_nop 0
	s_nop 0
	s_nop 0
	s_nop 0
	s_nop 0
	s_nop 0
	s_nop 0
	s_nop 0
	s_nop 0
	s_nop 0
	s_nop 0
	s_nop 0
	s_nop 0
	s_nop 0
	s_nop 0
	s_nop 0
	s_nop 0
	s_nop 0
	s_nop 0
	s_nop 0
	s_nop 0
	s_nop 0
	s_nop 0
	s_nop 0
	s_nop 0
	s_nop 0
	s_nop 0
	s_nop 0
	s_nop 0
	s_nop 0
	s_nop 0
	s_nop 0
	s_nop 0
	s_nop 0
	s_nop 0
	s_nop 0
	s_nop 0
	s_nop 0
	s_nop 0
	s_nop 0
	s_nop 0
	s_nop 0
	s_nop 0
	s_nop 0
	s_nop 0
	s_nop 0
	s_nop 0
	s_nop 0
	s_nop 0
	s_nop 0
	s_nop 0
	s_nop 0
	s_nop 0
	s_nop 0
	s_nop 0
	s_nop 0
	s_nop 0
	s_nop 0
	s_nop 0
	s_nop 0
	s_nop 0
	s_nop 0
	s_nop 0
	s_nop 0
	s_nop 0
	s_nop 0
	s_nop 0
	s_nop 0
	s_nop 0
	s_nop 0
	s_nop 0
	s_nop 0
	s_nop 0
	s_nop 0
	s_nop 0
	s_nop 0
	s_nop 0
	s_nop 0
	s_nop 0
	s_nop 0
	s_nop 0
	s_nop 0
	s_nop 0
	s_nop 0
	s_nop 0
	s_nop 0
	s_nop 0
	s_nop 0
	s_nop 0
	s_nop 0
	s_nop 0
	s_nop 0
	s_nop 0
	s_nop 0
	s_nop 0
	s_nop 0
	s_nop 0
	s_nop 0
	s_nop 0
	s_nop 0
	s_nop 0
	s_nop 0
	s_nop 0
	s_nop 0
	s_nop 0
	s_nop 0
	s_nop 0
	s_nop 0
	s_nop 0
	s_nop 0
	s_nop 0
	s_nop 0
	s_nop 0
	s_nop 0
	s_nop 0
	s_nop 0
	s_nop 0
	s_nop 0
	s_nop 0
	s_nop 0
	s_nop 0
	s_nop 0
	s_nop 0
	s_nop 0
	s_nop 0
	s_nop 0
	s_nop 0
	s_nop 0
	s_nop 0
	s_nop 0
	s_nop 0
	s_nop 0
	s_nop 0
	s_nop 0
	s_nop 0
	s_nop 0
	s_nop 0
	s_nop 0
	s_nop 0
	s_nop 0
	s_nop 0
	s_nop 0
	s_nop 0
	s_nop 0
	s_nop 0
	s_nop 0
	s_nop 0
	s_nop 0
	s_nop 0
	s_nop 0
	s_nop 0
	s_nop 0
	s_nop 0
	s_nop 0
	s_nop 0
	s_nop 0
	s_nop 0
	s_nop 0
	s_nop 0
	s_nop 0
	s_nop 0
	s_nop 0
	s_nop 0
	s_nop 0
	s_nop 0
	s_nop 0
	s_nop 0
	s_nop 0
	s_nop 0
	s_nop 0
	s_nop 0
	s_nop 0
	s_nop 0
	s_nop 0
	s_nop 0
	s_nop 0
	s_nop 0
	s_nop 0
	s_nop 0
	s_nop 0
	s_nop 0
	s_nop 0
	s_nop 0
	s_nop 0
	s_nop 0
	s_nop 0
	s_nop 0
	s_nop 0
	s_nop 0
	s_nop 0
	s_nop 0
	s_nop 0
	s_nop 0
	s_nop 0
	s_nop 0
	s_nop 0
	s_nop 0
	s_nop 0
	s_nop 0
	s_nop 0
	s_nop 0
	s_nop 0
	s_nop 0
	s_nop 0
	s_nop 0
	s_nop 0
	s_nop 0
	s_nop 0
	s_nop 0
	s_nop 0
	s_nop 0
	s_nop 0
	s_nop 0
	s_nop 0
	s_nop 0
	s_nop 0
	s_nop 0
	s_nop 0
	s_nop 0
	s_nop 0
	s_nop 0
	s_nop 0
	s_nop 0
	s_nop 0
	s_nop 0
	s_nop 0
	s_nop 0
	s_nop 0
	s_nop 0
	s_nop 0
	s_nop 0
	s_nop 0
	s_nop 0
	s_nop 0
	s_nop 0
	s_nop 0
	s_nop 0
	s_nop 0
	s_nop 0
	s_nop 0
	s_nop 0
	s_nop 0
	s_nop 0
	s_nop 0
	s_nop 0
	s_nop 0
	s_nop 0
	s_nop 0
	s_nop 0
	s_nop 0
	s_nop 0
	s_nop 0
	s_nop 0
	s_nop 0
	s_nop 0
	s_nop 0
	s_nop 0
	s_nop 0
	s_nop 0
	s_nop 0
	s_nop 0
	s_nop 0
	s_nop 0
	s_nop 0
	s_nop 0
	s_nop 0
	s_nop 0
	s_nop 0
	s_nop 0
	s_nop 0
	s_nop 0
	s_nop 0
	s_nop 0
	s_nop 0
	s_nop 0
	s_nop 0
	s_nop 0
	s_nop 0
	s_nop 0
	s_nop 0
	s_nop 0
	s_nop 0
	s_nop 0
	s_nop 0
	s_nop 0
	s_nop 0
	s_nop 0
	s_nop 0
	s_nop 0
	s_nop 0
	s_nop 0
	s_nop 0
	s_nop 0
	s_nop 0
	s_nop 0
	s_nop 0
	s_nop 0
	s_nop 0
	s_nop 0
	s_nop 0
	s_nop 0
	s_nop 0
	s_nop 0
	s_nop 0
	s_nop 0
	s_nop 0
	s_nop 0
	s_nop 0
	s_nop 0
	s_nop 0
	s_nop 0
	s_nop 0
	s_nop 0
	s_nop 0
	s_nop 0
	s_nop 0
	s_nop 0
	s_nop 0
	s_nop 0
	s_nop 0
	s_nop 0
	s_nop 0
	s_nop 0
	s_nop 0
	s_nop 0
	s_nop 0
	s_nop 0
	s_nop 0
	s_nop 0
	s_nop 0
	s_nop 0
	s_nop 0
	s_nop 0
	s_nop 0
	s_nop 0
	s_nop 0
	s_nop 0
	s_nop 0
	s_nop 0
	s_nop 0
	s_nop 0
	s_nop 0
	s_nop 0
	s_nop 0
	s_nop 0
	s_nop 0
	s_nop 0
	s_nop 0
	s_nop 0
	s_nop 0
	s_nop 0
	s_nop 0
	s_nop 0
	s_nop 0
	s_nop 0
	s_nop 0
	s_nop 0
	s_nop 0
	s_nop 0
	s_nop 0
	s_nop 0
	s_nop 0
	s_nop 0
	s_nop 0
	s_nop 0
	s_nop 0
	s_nop 0
	s_nop 0
	s_nop 0
	s_nop 0
	s_nop 0
	s_nop 0
	s_nop 0
	s_nop 0
	s_nop 0
	s_nop 0
	s_nop 0
	s_nop 0
	s_nop 0
	s_nop 0
	s_nop 0
	s_nop 0
	s_nop 0
	s_nop 0
	s_nop 0
	s_nop 0
	s_nop 0
	s_nop 0
	s_nop 0
	s_nop 0
	s_nop 0
	s_nop 0
	s_nop 0
	s_nop 0
	s_nop 0
	s_nop 0
	s_nop 0
	s_nop 0
	s_nop 0
	s_nop 0
	s_nop 0
	s_nop 0
